# v063 plus MLA cross-half row-max exchange by v_permlane32_swap instead of ds_bpermute
# speedup vs baseline: 1.0024x; 1.0024x over previous
; DI float fexp2(float x) { return __builtin_amdgcn_exp2f(x); }
;     ...
;             float mt = fmaxf(s[j][0], s[j][1]);
; #pragma unroll
;             for (int i = 2; i < 16; ++i) mt = fmaxf(mt, s[j][i]);
;             mt = fmaxf(mt, __shfl_xor(mt, 32));
;             if (MODE == 1) mt *= c2;
;             const float cand = fmaxf(mrun, mt);
;             if (__any(cand > mrun + 8.f)) {
;               const float alpha = fexp2(mrun - cand);
;               mrun = cand; lsum *= alpha;
; #pragma unroll
;               for (int i = 0; i < 16; ++i) { oacc[0][i] *= alpha; oacc[1][i] *= alpha; }
;             }
;             const float nm = -mrun;
; #pragma unroll
;             for (int i = 0; i < 16; ++i) {
;               const float p = (MODE == 1) ? fexp2(fmaf(s[j][i], c2, nm)) : fexp2(s[j][i] + nm);
;               lsum += p; s[j][i] = p;
.LBB0_830:
	s_or_b64 exec, exec, s[8:9]
	v_add_f32_e32 v128, v201, v209
	v_add_f32_e32 v128, v211, v128
	v_max_f32_e32 v129, v33, v33
	v_max_f32_e32 v130, v32, v32
	v_add_f32_e32 v128, v212, v128
	v_max_f32_e32 v129, v130, v129
	v_add_f32_e32 v128, v213, v128
	v_max3_f32 v129, v129, v34, v35
	v_add_f32_e32 v128, v214, v128
	v_max3_f32 v129, v129, v36, v37
	v_add_f32_e32 v128, v215, v128
	v_max3_f32 v129, v129, v38, v39
	v_add_f32_e32 v128, v216, v128
	v_max3_f32 v129, v129, v40, v41
	v_add_f32_e32 v128, v217, v128
	v_max3_f32 v129, v129, v42, v43
	v_add_f32_e32 v128, v218, v128
	v_max3_f32 v129, v129, v44, v45
	v_add_f32_e32 v128, v219, v128
	v_max3_f32 v130, v129, v46, v47
	v_add_f32_e32 v128, v220, v128
	v_mov_b32_e32 v131, v130
	v_mov_b32_e32 v231, v130
	s_nop 1
	v_permlane32_swap_b32_e32 v131, v231
	v_max_f32_e32 v131, v131, v231
	v_add_f32_e32 v128, v221, v128
	v_add_f32_e32 v128, v203, v128
	v_add_f32_e32 v128, v207, v128
	v_add_f32_e32 v128, v208, v128
	v_add_f32_e32 v129, v210, v128
	s_waitcnt lgkmcnt(0)
	v_max_f32_e32 v128, v131, v131
	v_max_f32_e32 v128, v130, v128
	v_mul_f32_e32 v128, 0x3e16c73f, v128
	v_max_f32_e32 v130, v202, v202
	v_max_f32_e32 v130, v130, v128
	v_add_f32_e32 v128, 0x41000000, v202
	v_cmp_gt_f32_e32 vcc, v130, v128
	s_cbranch_vccz .LBB0_853
	v_sub_f32_e32 v128, v202, v130
	v_exp_f32_e32 v128, v128
	v_mov_b32_e32 v202, v130
	v_mul_f32_e32 v129, v129, v128
	v_pk_mul_f32 v[30:31], v[30:31], v[128:129] op_sel_hi:[1,0]
	v_pk_mul_f32 v[28:29], v[28:29], v[128:129] op_sel_hi:[1,0]
	v_pk_mul_f32 v[26:27], v[26:27], v[128:129] op_sel_hi:[1,0]
	v_pk_mul_f32 v[24:25], v[24:25], v[128:129] op_sel_hi:[1,0]
	v_pk_mul_f32 v[22:23], v[22:23], v[128:129] op_sel_hi:[1,0]
	v_pk_mul_f32 v[20:21], v[20:21], v[128:129] op_sel_hi:[1,0]
	v_pk_mul_f32 v[18:19], v[18:19], v[128:129] op_sel_hi:[1,0]
	v_pk_mul_f32 v[16:17], v[16:17], v[128:129] op_sel_hi:[1,0]
	v_pk_mul_f32 v[14:15], v[14:15], v[128:129] op_sel_hi:[1,0]
	v_pk_mul_f32 v[12:13], v[12:13], v[128:129] op_sel_hi:[1,0]
	v_pk_mul_f32 v[10:11], v[10:11], v[128:129] op_sel_hi:[1,0]
	v_pk_mul_f32 v[8:9], v[8:9], v[128:129] op_sel_hi:[1,0]
	v_pk_mul_f32 v[6:7], v[6:7], v[128:129] op_sel_hi:[1,0]
	v_pk_mul_f32 v[4:5], v[4:5], v[128:129] op_sel_hi:[1,0]
	v_pk_mul_f32 v[2:3], v[2:3], v[128:129] op_sel_hi:[1,0]
	v_pk_mul_f32 v[0:1], v[0:1], v[128:129] op_sel_hi:[1,0]
	v_xor_b32_e32 v128, 0x80000000, v130

; DI float fexp2(float x) { return __builtin_amdgcn_exp2f(x); }
;     ...
;             float mt = fmaxf(s[j][0], s[j][1]);
; #pragma unroll
;             for (int i = 2; i < 16; ++i) mt = fmaxf(mt, s[j][i]);
;             mt = fmaxf(mt, __shfl_xor(mt, 32));
;             if (MODE == 1) mt *= c2;
;             const float cand = fmaxf(mrun, mt);
;             if (__any(cand > mrun + 8.f)) {
;               const float alpha = fexp2(mrun - cand);
;               mrun = cand; lsum *= alpha;
; #pragma unroll
;               for (int i = 0; i < 16; ++i) { oacc[0][i] *= alpha; oacc[1][i] *= alpha; }
.LBB0_837:
	s_or_b64 exec, exec, s[8:9]
	v_max_f32_e32 v202, v49, v49
	v_max_f32_e32 v205, v48, v48
	v_max_f32_e32 v202, v205, v202
	v_max3_f32 v202, v202, v50, v51
	v_max3_f32 v202, v202, v52, v53
	v_max3_f32 v202, v202, v54, v55
	v_and_b32_e32 v208, 64, v182
	v_max3_f32 v202, v202, v56, v57
	v_xor_b32_e32 v205, 32, v182
	v_add_u32_e32 v208, 64, v208
	v_max3_f32 v202, v202, v58, v59
	v_cmp_lt_i32_e32 vcc, v205, v208
	v_max3_f32 v202, v202, v60, v61
	v_max3_f32 v202, v202, v62, v63
	v_cndmask_b32_e32 v205, v182, v205, vcc
	v_lshlrev_b32_e32 v205, 2, v205
	v_mov_b32_e32 v208, v202
	v_mov_b32_e32 v231, v202
	s_nop 1
	v_permlane32_swap_b32_e32 v208, v231
	v_max_f32_e32 v208, v208, v231
	s_waitcnt lgkmcnt(0)
	v_max_f32_e32 v208, v208, v208
	v_max_f32_e32 v202, v202, v208
	v_mul_f32_e32 v202, 0x3e16c73f, v202
	v_max_f32_e32 v208, v203, v203
	v_max_f32_e32 v202, v208, v202
	v_add_f32_e32 v208, 0x41000000, v203
	v_cmp_gt_f32_e32 vcc, v202, v208
	s_cbranch_vccz .LBB0_839
	v_sub_f32_e32 v203, v203, v202
	v_exp_f32_e32 v208, v203
	s_nop 0
	v_mul_f32_e32 v201, v201, v208
	v_pk_mul_f32 v[30:31], v[30:31], v[208:209] op_sel_hi:[1,0]
	v_pk_mul_f32 v[28:29], v[28:29], v[208:209] op_sel_hi:[1,0]
	v_pk_mul_f32 v[26:27], v[26:27], v[208:209] op_sel_hi:[1,0]
	v_pk_mul_f32 v[24:25], v[24:25], v[208:209] op_sel_hi:[1,0]
	v_pk_mul_f32 v[22:23], v[22:23], v[208:209] op_sel_hi:[1,0]
	v_pk_mul_f32 v[20:21], v[20:21], v[208:209] op_sel_hi:[1,0]
	v_pk_mul_f32 v[18:19], v[18:19], v[208:209] op_sel_hi:[1,0]
	v_pk_mul_f32 v[16:17], v[16:17], v[208:209] op_sel_hi:[1,0]
	v_pk_mul_f32 v[14:15], v[14:15], v[208:209] op_sel_hi:[1,0]
	v_pk_mul_f32 v[12:13], v[12:13], v[208:209] op_sel_hi:[1,0]
	v_pk_mul_f32 v[10:11], v[10:11], v[208:209] op_sel_hi:[1,0]
	v_pk_mul_f32 v[8:9], v[8:9], v[208:209] op_sel_hi:[1,0]
	v_pk_mul_f32 v[6:7], v[6:7], v[208:209] op_sel_hi:[1,0]
	v_pk_mul_f32 v[4:5], v[4:5], v[208:209] op_sel_hi:[1,0]
	v_pk_mul_f32 v[2:3], v[2:3], v[208:209] op_sel_hi:[1,0]
	v_pk_mul_f32 v[0:1], v[0:1], v[208:209] op_sel_hi:[1,0]
	s_branch .LBB0_840

; DI float fexp2(float x) { return __builtin_amdgcn_exp2f(x); }
;     ...
;             float mt = fmaxf(s[j][0], s[j][1]);
; #pragma unroll
;             for (int i = 2; i < 16; ++i) mt = fmaxf(mt, s[j][i]);
;             mt = fmaxf(mt, __shfl_xor(mt, 32));
;             if (MODE == 1) mt *= c2;
;             const float cand = fmaxf(mrun, mt);
;             if (__any(cand > mrun + 8.f)) {
;               const float alpha = fexp2(mrun - cand);
;               mrun = cand; lsum *= alpha;
; #pragma unroll
;               for (int i = 0; i < 16; ++i) { oacc[0][i] *= alpha; oacc[1][i] *= alpha; }
;             }
;             const float nm = -mrun;
; #pragma unroll
;             for (int i = 0; i < 16; ++i) {
;               const float p = (MODE == 1) ? fexp2(fmaf(s[j][i], c2, nm)) : fexp2(s[j][i] + nm);
;               lsum += p; s[j][i] = p;
.LBB0_842:
	s_or_b64 exec, exec, s[8:9]
	v_add_f32_e32 v128, v201, v210
	v_add_f32_e32 v128, v212, v128
	v_max_f32_e32 v129, v33, v33
	v_max_f32_e32 v130, v32, v32
	v_add_f32_e32 v128, v213, v128
	v_max_f32_e32 v129, v130, v129
	v_add_f32_e32 v128, v214, v128
	v_max3_f32 v129, v129, v34, v35
	v_add_f32_e32 v128, v215, v128
	v_max3_f32 v129, v129, v36, v37
	v_add_f32_e32 v128, v216, v128
	v_max3_f32 v129, v129, v38, v39
	v_add_f32_e32 v128, v217, v128
	v_max3_f32 v129, v129, v40, v41
	v_add_f32_e32 v128, v218, v128
	v_max3_f32 v129, v129, v42, v43
	v_add_f32_e32 v128, v219, v128
	v_max3_f32 v129, v129, v44, v45
	v_add_f32_e32 v128, v220, v128
	v_max3_f32 v130, v129, v46, v47
	v_add_f32_e32 v128, v221, v128
	v_mov_b32_e32 v131, v130
	v_mov_b32_e32 v231, v130
	s_nop 1
	v_permlane32_swap_b32_e32 v131, v231
	v_max_f32_e32 v131, v131, v231
	v_add_f32_e32 v128, v222, v128
	v_add_f32_e32 v128, v203, v128
	v_add_f32_e32 v128, v208, v128
	v_add_f32_e32 v128, v209, v128
	v_add_f32_e32 v129, v211, v128
	s_waitcnt lgkmcnt(0)
	v_max_f32_e32 v128, v131, v131
	v_max_f32_e32 v128, v130, v128
	v_mul_f32_e32 v128, 0x3e16c73f, v128
	v_max_f32_e32 v130, v202, v202
	v_max_f32_e32 v130, v130, v128
	v_add_f32_e32 v128, 0x41000000, v202
	v_cmp_gt_f32_e32 vcc, v130, v128
	s_cbranch_vccz .LBB0_844
	v_sub_f32_e32 v128, v202, v130
	v_exp_f32_e32 v128, v128
	v_mov_b32_e32 v202, v130
	v_mul_f32_e32 v129, v129, v128
	v_pk_mul_f32 v[30:31], v[30:31], v[128:129] op_sel_hi:[1,0]
	v_pk_mul_f32 v[28:29], v[28:29], v[128:129] op_sel_hi:[1,0]
	v_pk_mul_f32 v[26:27], v[26:27], v[128:129] op_sel_hi:[1,0]
	v_pk_mul_f32 v[24:25], v[24:25], v[128:129] op_sel_hi:[1,0]
	v_pk_mul_f32 v[22:23], v[22:23], v[128:129] op_sel_hi:[1,0]
	v_pk_mul_f32 v[20:21], v[20:21], v[128:129] op_sel_hi:[1,0]
	v_pk_mul_f32 v[18:19], v[18:19], v[128:129] op_sel_hi:[1,0]
	v_pk_mul_f32 v[16:17], v[16:17], v[128:129] op_sel_hi:[1,0]
	v_pk_mul_f32 v[14:15], v[14:15], v[128:129] op_sel_hi:[1,0]
	v_pk_mul_f32 v[12:13], v[12:13], v[128:129] op_sel_hi:[1,0]
	v_pk_mul_f32 v[10:11], v[10:11], v[128:129] op_sel_hi:[1,0]
	v_pk_mul_f32 v[8:9], v[8:9], v[128:129] op_sel_hi:[1,0]
	v_pk_mul_f32 v[6:7], v[6:7], v[128:129] op_sel_hi:[1,0]
	v_pk_mul_f32 v[4:5], v[4:5], v[128:129] op_sel_hi:[1,0]
	v_pk_mul_f32 v[2:3], v[2:3], v[128:129] op_sel_hi:[1,0]
	v_pk_mul_f32 v[0:1], v[0:1], v[128:129] op_sel_hi:[1,0]
	v_xor_b32_e32 v128, 0x80000000, v130
	s_branch .LBB0_845

; DI float fexp2(float x) { return __builtin_amdgcn_exp2f(x); }
;     ...
;             float mt = fmaxf(s[j][0], s[j][1]);
; #pragma unroll
;             for (int i = 2; i < 16; ++i) mt = fmaxf(mt, s[j][i]);
;             mt = fmaxf(mt, __shfl_xor(mt, 32));
;             if (MODE == 1) mt *= c2;
;             const float cand = fmaxf(mrun, mt);
;             if (__any(cand > mrun + 8.f)) {
;               const float alpha = fexp2(mrun - cand);
;               mrun = cand; lsum *= alpha;
; #pragma unroll
;               for (int i = 0; i < 16; ++i) { oacc[0][i] *= alpha; oacc[1][i] *= alpha; }
.LBB0_850:
	s_or_b64 exec, exec, s[8:9]
	v_max_f32_e32 v202, v49, v49
	v_max_f32_e32 v204, v48, v48
	v_max_f32_e32 v202, v204, v202
	v_max3_f32 v202, v202, v50, v51
	v_max3_f32 v202, v202, v52, v53
	v_max3_f32 v202, v202, v54, v55
	v_and_b32_e32 v207, 64, v182
	v_max3_f32 v202, v202, v56, v57
	v_xor_b32_e32 v204, 32, v182
	v_add_u32_e32 v207, 64, v207
	v_max3_f32 v202, v202, v58, v59
	v_cmp_lt_i32_e32 vcc, v204, v207
	v_max3_f32 v202, v202, v60, v61
	v_max3_f32 v202, v202, v62, v63
	v_cndmask_b32_e32 v204, v182, v204, vcc
	v_lshlrev_b32_e32 v204, 2, v204
	v_mov_b32_e32 v207, v202
	v_mov_b32_e32 v231, v202
	s_nop 1
	v_permlane32_swap_b32_e32 v207, v231
	v_max_f32_e32 v207, v207, v231
	s_waitcnt lgkmcnt(0)
	v_max_f32_e32 v207, v207, v207
	v_max_f32_e32 v202, v202, v207
	v_mul_f32_e32 v202, 0x3e16c73f, v202
	v_max_f32_e32 v207, v203, v203
	v_max_f32_e32 v202, v207, v202
	v_add_f32_e32 v207, 0x41000000, v203
	v_cmp_gt_f32_e32 vcc, v202, v207
	s_cbranch_vccz .LBB0_854
	v_sub_f32_e32 v203, v203, v202
	v_exp_f32_e32 v208, v203
	s_nop 0
	v_mul_f32_e32 v201, v201, v208
	v_pk_mul_f32 v[30:31], v[30:31], v[208:209] op_sel_hi:[1,0]
	v_pk_mul_f32 v[28:29], v[28:29], v[208:209] op_sel_hi:[1,0]
	v_pk_mul_f32 v[26:27], v[26:27], v[208:209] op_sel_hi:[1,0]
	v_pk_mul_f32 v[24:25], v[24:25], v[208:209] op_sel_hi:[1,0]
	v_pk_mul_f32 v[22:23], v[22:23], v[208:209] op_sel_hi:[1,0]
	v_pk_mul_f32 v[20:21], v[20:21], v[208:209] op_sel_hi:[1,0]
	v_pk_mul_f32 v[18:19], v[18:19], v[208:209] op_sel_hi:[1,0]
	v_pk_mul_f32 v[16:17], v[16:17], v[208:209] op_sel_hi:[1,0]
	v_pk_mul_f32 v[14:15], v[14:15], v[208:209] op_sel_hi:[1,0]
	v_pk_mul_f32 v[12:13], v[12:13], v[208:209] op_sel_hi:[1,0]
	v_pk_mul_f32 v[10:11], v[10:11], v[208:209] op_sel_hi:[1,0]
	v_pk_mul_f32 v[8:9], v[8:9], v[208:209] op_sel_hi:[1,0]
	v_pk_mul_f32 v[6:7], v[6:7], v[208:209] op_sel_hi:[1,0]
	v_pk_mul_f32 v[4:5], v[4:5], v[208:209] op_sel_hi:[1,0]
	v_pk_mul_f32 v[2:3], v[2:3], v[208:209] op_sel_hi:[1,0]
	v_pk_mul_f32 v[0:1], v[0:1], v[208:209] op_sel_hi:[1,0]
	s_branch .LBB0_855
